# attention unit prologue: key-bias global->LDS copy issued as one batch (up to 4 passes in flight) instead of one round trip per pass
# baseline (speedup 1.0000x reference)
; template<int THRL> __device__ __forceinline__ void attn_unit(int b,int h,int qb,const bf16*Q,const bf16*__restrict__ K,const bf16*__restrict__ V,bf16*O,const float*__restrict__ CK,const float*__restrict__ KMX,const float*__restrict__ QSV,char*shm){
;     ...
;   { float*ckw=(float*)(shm+LDS_CK); const int nk4=NT*(KVBLK/4);
;     for(int i=tid;i<nk4;i+=NW*64){ const f32x4v c4=*reinterpret_cast<const f32x4v*>(CK+4*i); *reinterpret_cast<f32x4v*>(ckw+4*i)=c4; } }
.LBB0_716:
	s_add_i32 s4, s72, -4
	s_min_i32 s74, s16, s4
	s_and_b32 s6, s74, -2
	s_sub_i32 s64, s72, s6
	s_lshl_b32 s7, s64, 4
	v_cmp_gt_i32_e32 vcc, s7, v116
	s_and_saveexec_b64 s[4:5], vcc
	s_cbranch_execz .LBB0_719
	s_lshl_b32 s16, s6, 6
	s_ashr_i32 s17, s16, 31
	s_lshl_b64 s[16:17], s[16:17], 2
	s_add_u32 s14, s14, s16
	s_addc_u32 s15, s15, s17
	v_lshl_add_u32 v2, v116, 4, s50
	v_lshlrev_b32_e32 v0, 4, v116
	global_load_dwordx4 v[4:7], v0, s[14:15]
	v_add_u32_e32 v3, 0x200, v116
	v_cmp_gt_i32_e32 vcc, s7, v3
	v_add_u32_e32 v1, 0x2000, v0
	s_and_b64 exec, exec, vcc
	s_cbranch_execz .Lck_ld_done
	global_load_dwordx4 v[8:11], v1, s[14:15]
	v_add_u32_e32 v3, 0x400, v116
	v_cmp_gt_i32_e32 vcc, s7, v3
	v_add_u32_e32 v1, 0x4000, v0
	s_and_b64 exec, exec, vcc
	s_cbranch_execz .Lck_ld_done
	global_load_dwordx4 v[12:15], v1, s[14:15]
	v_add_u32_e32 v3, 0x600, v116
	v_cmp_gt_i32_e32 vcc, s7, v3
	v_add_u32_e32 v1, 0x6000, v0
	s_and_b64 exec, exec, vcc
	s_cbranch_execz .Lck_ld_done
	global_load_dwordx4 v[16:19], v1, s[14:15]
.Lck_ld_done:
	s_mov_b64 exec, s[4:5]
	v_cmp_gt_i32_e32 vcc, s7, v116
	s_and_b64 exec, exec, vcc
	s_waitcnt vmcnt(0)
	ds_write_b128 v2, v[4:7]
	v_add_u32_e32 v3, 0x200, v116
	v_cmp_gt_i32_e32 vcc, s7, v3
	s_and_b64 exec, exec, vcc
	s_cbranch_execz .LBB0_719
	ds_write_b128 v2, v[8:11] offset:8192
	v_add_u32_e32 v3, 0x400, v116
	v_cmp_gt_i32_e32 vcc, s7, v3
	s_and_b64 exec, exec, vcc
	s_cbranch_execz .LBB0_719
	ds_write_b128 v2, v[12:15] offset:16384
	v_add_u32_e32 v3, 0x600, v116
	v_cmp_gt_i32_e32 vcc, s7, v3
	s_and_b64 exec, exec, vcc
	s_cbranch_execz .LBB0_719
	ds_write_b128 v2, v[16:19] offset:24576
